# mixer work queue: next item's pop issued late inside the current item (diff last tile / fox epilogue / gmlp+conv start) and consumed at loop top
# baseline (speedup 1.0000x reference)
; #define LAS __attribute__((address_space(3)))
; __device__ __forceinline__ unsigned xb_add(unsigned* p, unsigned v) { return __hip_atomic_fetch_add(p, v, __ATOMIC_RELAXED, __HIP_MEMORY_SCOPE_AGENT); }
; __device__ __forceinline__ unsigned xb_xcc_id() { return (unsigned)__builtin_amdgcn_s_getreg((3 << 11) | 20) & 0xFu; }
; __device__ __forceinline__ XcdBarrier xcd_barrier_post(unsigned* bar, volatile LAS unsigned* st) {
;     XcdBarrier b; b.bar = bar; b.x = xb_xcc_id(); b.st = st;
;     if (threadIdx.x == 0) (void)xb_add(&bar[XB_XCNT(b.x)], 1u);
;     return b;
; }
; __global__ void __launch_bounds__(512, 2) fwd_kernel(Args A_unused) {
;     CA* const P0 = (CA*)__builtin_amdgcn_kernarg_segment_ptr();
;     extern __shared__ __attribute__((aligned(16))) unsigned char lds_raw[];
;     LAS unsigned char* lds = (LAS unsigned char*)lds_raw;
;     cg::grid_group grid = cg::this_grid();
;     const int ph_lo = P0->ph_lo, ph_hi = P0->ph_hi;
;     if (threadIdx.x < 16) ((LAS unsigned*)(lds + LDS_MAIN))[threadIdx.x] = 0u;
;     __syncthreads();
;     XcdBarrier xbar = xcd_barrier_post((unsigned*)(P0->ws + WS_XBAR), (volatile LAS unsigned*)(lds + LDS_MAIN + 16));
_Z10fwd_kernel4Args:
	s_mov_b32 s92, s2
	s_load_dwordx2 s[2:3], s[0:1], 0xd0
	v_and_b32_e32 v179, 0x3ff, v0
	v_mov_b32_e32 v239, -1
	v_cmp_gt_u32_e32 vcc, 16, v179
	s_waitcnt lgkmcnt(0)
	v_writelane_b32 v238, s2, 0
	s_nop 1
	v_writelane_b32 v238, s3, 1
	s_add_u32 s2, s0, 0xd8
	v_writelane_b32 v238, s0, 2
	s_addc_u32 s3, s1, 0
	s_nop 0
	v_writelane_b32 v238, s1, 3
	v_writelane_b32 v238, s2, 4
	s_nop 1
	v_writelane_b32 v238, s3, 5
	s_and_saveexec_b64 s[0:1], vcc
	v_lshl_add_u32 v1, v179, 2, 0
	v_add_u32_e32 v1, 0x20000, v1
	v_mov_b32_e32 v2, 0
	ds_write_b32 v1, v2
	s_or_b64 exec, exec, s[0:1]
	v_readlane_b32 s0, v238, 2
	v_readlane_b32 s1, v238, 3
	s_load_dwordx2 s[2:3], s[0:1], 0xd8
	s_waitcnt lgkmcnt(0)
	s_barrier
	s_load_dwordx2 s[0:1], s[0:1], 0xc8
	v_writelane_b32 v238, s2, 6
	s_getreg_b32 s4, hwreg(HW_REG_XCC_ID, 0, 4)
	v_cmp_eq_u32_e64 s[6:7], 0, v179
	v_writelane_b32 v238, s3, 7
	s_waitcnt lgkmcnt(0)
	s_add_u32 s2, s0, 0x4000
	s_addc_u32 s3, s1, 0
	s_and_b32 s8, s4, 15
	s_mov_b64 s[4:5], exec
	v_writelane_b32 v238, s6, 8
	s_nop 1
	v_writelane_b32 v238, s7, 9
	s_and_b64 s[6:7], s[4:5], s[6:7]
	s_mov_b64 exec, s[6:7]
	s_cbranch_execz .LBB0_5
	s_mov_b64 s[6:7], exec
	v_mbcnt_lo_u32_b32 v1, s6, 0
	v_mbcnt_hi_u32_b32 v1, s7, v1
	v_cmp_eq_u32_e32 vcc, 0, v1
	s_and_b64 s[10:11], exec, vcc
	s_mov_b64 exec, s[10:11]
	s_cbranch_execz .LBB0_5
	s_and_b32 s10, s92, 7
	s_lshl_b32 s10, s10, 2
	s_lshl_b32 s11, 1, s8
	v_mov_b32_e32 v3, s10
	v_mov_b32_e32 v4, s11
	s_nop 0
	global_atomic_or v4, v3, v4, s[2:3] sc0
	s_waitcnt vmcnt(0)
	s_lshl_b32 s9, s8, 8
	s_bcnt1_i32_b64 s6, s[6:7]
	v_mov_b32_e32 v1, s9
	v_mov_b32_e32 v2, s6
	global_atomic_add v1, v2, s[2:3] offset:1024

; __device__ __forceinline__ unsigned pk2(float lo, float hi) { f32x2_t v = {lo, hi}; bf16x2_t b = __builtin_convertvector(v, bf16x2_t); return __builtin_bit_cast(unsigned, b); }
; template <bool DIFF>
; __device__ __forceinline__ void attn_unit(CA& A, int l, int b, int hh, int qb, LAS unsigned char* lds, float lam, float lam_init) {
;     ...
;     const float inv = 1.0f / ol[0];
;     const size_t orow = (size_t)b * SEQ + q0 + wq + r32;
;     if (!DIFF) {
; #pragma unroll
;         for (int dt = 0; dt < 2; ++dt)
; #pragma unroll
;             for (int g = 0; g < 4; ++g) {
;                 v2u w; w.x = pk2(o[dt][4 * g] * inv, o[dt][4 * g + 1] * inv); w.y = pk2(o[dt][4 * g + 2] * inv, o[dt][4 * g + 3] * inv);
;                 *(v2u*)(MIX + orow * DM + 768 + hh * 64 + 32 * dt + 8 * g + 4 * hi) = w;
;             }
; __device__ __forceinline__ void mix_phase(CA& A0, int l, LAS unsigned char* lds) {
;     ...
;     for (;;) {
;         __syncthreads();
;         if (tid == 0) *slot = (int)atomicAdd(counter, 1u);
;         __syncthreads();
;         const int it = *slot;
.LBB0_657:
	s_waitcnt vmcnt(0)
	s_mov_b64 s[12:13], exec
	v_readlane_b32 s14, v236, 5
	v_readlane_b32 s15, v236, 6
	s_nop 1
	s_and_b64 s[14:15], s[12:13], s[14:15]
	s_mov_b64 exec, s[14:15]
	s_cbranch_execz .Lmy_pf_fox_x
	v_readlane_b32 s14, v236, 3
	v_readlane_b32 s15, v236, 4
	v_mov_b32_e32 v239, 1
	s_nop 4
	global_atomic_add v239, v0, v239, s[14:15] sc0
.Lmy_pf_fox_x:
	s_mov_b64 exec, s[12:13]
	v_div_scale_f32 v1, s[4:5], v48, v48, 1.0
	v_rcp_f32_e32 v2, v1
	s_lshl_b32 s4, s25, 12
	s_add_i32 s24, s24, s4
	s_ashr_i32 s4, s20, 31
	v_fma_f32 v3, -v1, v2, 1.0
	v_fmac_f32_e32 v2, v3, v2
	v_div_scale_f32 v3, vcc, 1.0, v48, 1.0
	v_mul_f32_e32 v4, v3, v2
	v_fma_f32 v5, -v1, v4, v3
	v_fmac_f32_e32 v4, v5, v2
	s_add_u32 s5, s20, s24
	v_fma_f32 v1, -v1, v4, v3
	s_addc_u32 s4, s4, 0
	v_div_fmas_f32 v1, v1, v2, v4
	v_or_b32_e32 v4, s5, v137
	v_mov_b32_e32 v5, s4
	v_lshlrev_b64 v[4:5], 11, v[4:5]
	v_lshl_add_u64 v[4:5], s[8:9], 0, v[4:5]
	s_lshl_b32 s40, s28, 1
	s_mov_b32 s5, s41
	v_writelane_b32 v237, s4, 58
	v_lshl_add_u64 v[4:5], v[4:5], 0, s[40:41]
	v_lshlrev_b32_e32 v6, 1, v142
	v_mov_b32_e32 v7, v0
	v_writelane_b32 v237, s5, 59
	v_lshl_add_u64 v[4:5], v[4:5], 0, v[6:7]
	s_mov_b64 s[4:5], 0x7500600
	v_div_fixup_f32 v2, v1, v48, 1.0
	v_lshl_add_u64 v[6:7], v[4:5], 0, s[4:5]
	s_mov_b32 s4, 0x7500000
	v_pk_mul_f32 v[8:9], v[32:33], v[2:3] op_sel_hi:[1,0]
	v_pk_mul_f32 v[10:11], v[34:35], v[2:3] op_sel_hi:[1,0]
	v_add_co_u32_e32 v4, vcc, s4, v4
	v_cvt_pk_bf16_f32 v8, v8, v9
	v_cvt_pk_bf16_f32 v9, v10, v11
	v_addc_co_u32_e32 v5, vcc, 0, v5, vcc
	global_store_dwordx2 v[4:5], v[8:9], off offset:1536
	v_pk_mul_f32 v[4:5], v[36:37], v[2:3] op_sel_hi:[1,0]
	v_pk_mul_f32 v[8:9], v[38:39], v[2:3] op_sel_hi:[1,0]
	v_cvt_pk_bf16_f32 v4, v4, v5
	v_cvt_pk_bf16_f32 v5, v8, v9
	global_store_dwordx2 v[6:7], v[4:5], off offset:16
	v_pk_mul_f32 v[4:5], v[40:41], v[2:3] op_sel_hi:[1,0]
	v_pk_mul_f32 v[8:9], v[42:43], v[2:3] op_sel_hi:[1,0]
	v_cvt_pk_bf16_f32 v4, v4, v5
	v_cvt_pk_bf16_f32 v5, v8, v9
	global_store_dwordx2 v[6:7], v[4:5], off offset:32
	v_pk_mul_f32 v[4:5], v[44:45], v[2:3] op_sel_hi:[1,0]
	v_pk_mul_f32 v[8:9], v[46:47], v[2:3] op_sel_hi:[1,0]
	v_cvt_pk_bf16_f32 v4, v4, v5
	v_cvt_pk_bf16_f32 v5, v8, v9
	global_store_dwordx2 v[6:7], v[4:5], off offset:48
	v_pk_mul_f32 v[4:5], v[16:17], v[2:3] op_sel_hi:[1,0]
	v_pk_mul_f32 v[8:9], v[18:19], v[2:3] op_sel_hi:[1,0]
	v_cvt_pk_bf16_f32 v4, v4, v5
	v_cvt_pk_bf16_f32 v5, v8, v9
	global_store_dwordx2 v[6:7], v[4:5], off offset:64
	v_pk_mul_f32 v[4:5], v[20:21], v[2:3] op_sel_hi:[1,0]
	v_pk_mul_f32 v[8:9], v[22:23], v[2:3] op_sel_hi:[1,0]
	v_cvt_pk_bf16_f32 v4, v4, v5
	v_cvt_pk_bf16_f32 v5, v8, v9
	global_store_dwordx2 v[6:7], v[4:5], off offset:80
	v_pk_mul_f32 v[4:5], v[24:25], v[2:3] op_sel_hi:[1,0]
	v_pk_mul_f32 v[8:9], v[26:27], v[2:3] op_sel_hi:[1,0]
	v_cvt_pk_bf16_f32 v4, v4, v5
	v_cvt_pk_bf16_f32 v5, v8, v9
	global_store_dwordx2 v[6:7], v[4:5], off offset:96
	v_pk_mul_f32 v[4:5], v[28:29], v[2:3] op_sel_hi:[1,0]
	v_pk_mul_f32 v[2:3], v[30:31], v[2:3] op_sel_hi:[1,0]
	v_cvt_pk_bf16_f32 v4, v4, v5
	v_cvt_pk_bf16_f32 v5, v2, v3
	global_store_dwordx2 v[6:7], v[4:5], off offset:112

; __device__ __forceinline__ void mix_phase(CA& A0, int l, LAS unsigned char* lds) {
;     ...
;     for (;;) {
;         __syncthreads();
;         if (tid == 0) *slot = (int)atomicAdd(counter, 1u);
;         __syncthreads();
;         const int it = *slot;
.LBB0_660:
	s_barrier
	s_and_saveexec_b64 s[4:5], s[12:13]
	s_cbranch_execz .LBB0_664
	s_waitcnt vmcnt(0)
	v_readfirstlane_b32 s6, v239
	v_mov_b32_e32 v239, -1
	v_mov_b32_e32 v1, 0
	s_nop 1
	s_cmp_eq_u32 s6, -1
	s_cbranch_scc0 .Lmy_q_have
	s_mov_b64 s[8:9], exec
	v_mbcnt_lo_u32_b32 v1, s8, 0
	v_mbcnt_hi_u32_b32 v1, s9, v1
	v_cmp_eq_u32_e32 vcc, 0, v1
	s_and_saveexec_b64 s[6:7], vcc
	s_cbranch_execz .LBB0_663
	s_bcnt1_i32_b64 s8, s[8:9]
	v_mov_b32_e32 v2, s8
	v_readlane_b32 s8, v236, 3
	v_readlane_b32 s9, v236, 4
	s_nop 4
	global_atomic_add v2, v0, v2, s[8:9] sc0

; #define LAS __attribute__((address_space(3)))
; __device__ __forceinline__ int otid() { int t = (int)threadIdx.x; asm volatile("" : "+v"(t)); return t; }
; __device__ __forceinline__ void conv_unit(CA& A, int l, int u, LAS unsigned char* lds) {
;     const int tid = otid(), lane = tid & 63, wid = tid >> 6;
;     const int b = u >> 6, t0 = (u & 63) * 64;
;     const bf16_t* Zb = (const bf16_t*)(A.ws + WS_Z) + (size_t)b * SEQ * ZC;
;     bf16_t* MIX = (bf16_t*)(A.ws + WS_MIX);
;     LAS float* Y = (LAS float*)lds;
;     const int c = tid & 255, half = tid >> 8;
;     float w[31];
; #pragma unroll
;     for (int j = 0; j < 31; ++j) w[j] = A.conv_w[(size_t)(l * 31 + j) * 256 + c];
;     const float bias = A.conv_b[l * 256 + c];
;     const f32x4 g4 = *(const f32x4*)(A.conv_norm_g + l * 256 + 4 * lane), b4 = *(const f32x4*)(A.conv_norm_b + l * 256 + 4 * lane);
;     {
;         v4u araw[6], graw[6];
; #pragma unroll
;         for (int k = 0; k < 6; ++k) { const int idx = tid + 512 * k, r = idx >> 5, ch = idx & 31, t = t0 - 30 + r;
;             araw[k] = (v4u){0u, 0u, 0u, 0u}; graw[k] = (v4u){0u, 0u, 0u, 0u};
;             if (idx < 94 * 32 && t >= 0) { araw[k] = *(const v4u*)(Zb + (size_t)t * ZC + CONV0 + 8 * ch); graw[k] = *(const v4u*)(Zb + (size_t)t * ZC + CONV0 + 256 + 8 * ch); } }
; __device__ __forceinline__ void mix_phase(CA& A0, int l, LAS unsigned char* lds) {
;     ...
;         const int it = *slot;
;         if (it >= MIX_ITEMS) break;
;         asm volatile("" : "+s"(l));
;         CA* Pq = &A0; asm volatile("" : "+s"(Pq)); CA& A = *Pq;
;         int ait = -1;
;         if (it < 256) ait = it; else if (it >= 256 + MIX_GMLP_ITEMS + MIX_CONV_ITEMS) ait = it - MIX_GMLP_ITEMS - MIX_CONV_ITEMS;
;         if (ait >= 0) {
;             const int level = 15 - ait / 48, r = ait % 48, grp = r / 16, bh = r % 16;
;             if (grp == 0) {
;  attn_unit<false>(A, l, bh >> 2, bh & 3, level, lds, lam, lam_init);
;  }
;             else {
;  attn_unit<true>(A, l, bh >> 2, bh & 3, grp == 1 ? 2 * level + 1 : 2 * level, lds, lam, lam_init);
;  }
;         } else if (it < 256 + MIX_GMLP_ITEMS) {
;  gmlp_unit(A, l, it - 256, lds);
;  }
;         else {
;  conv_unit(A, l, it - 256 - MIX_GMLP_ITEMS, lds);
.Lmy_q_have:
	v_add_u32_e32 v1, s6, v1
	s_add_i32 s6, 0, 0x20000
	v_mov_b32_e32 v2, s6
	ds_write_b32 v2, v1
.LBB0_664:
	s_or_b64 exec, exec, s[4:5]
	s_add_i32 s4, 0, 0x20000
	v_mov_b32_e32 v1, s4
	s_waitcnt lgkmcnt(0)
	s_barrier
	ds_read_b32 v1, v1
	s_movk_i32 s4, 0x47f
	s_waitcnt lgkmcnt(0)
	v_cmp_lt_i32_e32 vcc, s4, v1
	v_readfirstlane_b32 s37, v1
	s_mov_b64 s[4:5], -1
	s_cbranch_vccnz .LBB0_659
	s_add_i32 s4, s37, 0xffffff00
	s_cmp_lt_u32 s4, 0x180
	s_cbranch_scc0 .Lmy_pf_mid_skip
	s_mov_b64 s[6:7], exec
	v_readlane_b32 s8, v236, 5
	v_readlane_b32 s9, v236, 6
	s_nop 1
	s_and_b64 s[8:9], s[6:7], s[8:9]
	s_mov_b64 exec, s[8:9]
	s_cbranch_execz .Lmy_pf_mid_x
	v_readlane_b32 s8, v236, 3
	v_readlane_b32 s9, v236, 4
	v_mov_b32_e32 v239, 1
	s_nop 4
	global_atomic_add v239, v0, v239, s[8:9] sc0
.Lmy_pf_mid_x:
	s_mov_b64 exec, s[6:7]
.Lmy_pf_mid_skip:
	s_add_i32 s12, s37, 0xfffffe80
	s_cmpk_gt_i32 s37, 0x27f
	s_cselect_b32 s4, s12, -1
	s_cmpk_lt_i32 s37, 0x100
	v_readlane_b32 s34, v237, 63
	s_cselect_b32 s20, s37, s4
	v_readlane_b32 s35, v236, 0
	s_cmp_lt_i32 s20, 0
	s_mov_b64 s[4:5], -1
	s_cbranch_scc0 .LBB0_738
	s_cmpk_gt_i32 s37, 0x17f
	s_cbranch_scc0 .LBB0_686
	v_mov_b32_e32 v62, v179
	s_load_dwordx8 s[4:11], s[34:35], 0x70
	v_lshlrev_b32_sdwa v58, v223, v62 dst_sel:DWORD dst_unused:UNUSED_PAD src0_sel:DWORD src1_sel:BYTE_0
	v_mov_b32_e32 v59, v0
	s_load_dwordx2 s[16:17], s[34:35], 0xc8
	v_readlane_b32 s14, v237, 58
	s_waitcnt lgkmcnt(0)
	v_mov_b32_e32 v2, s6
	s_mul_i32 s6, s88, 31
	v_mov_b32_e32 v3, s7
	s_ashr_i32 s7, s6, 31
	v_lshl_add_u64 v[4:5], s[4:5], 0, v[58:59]
	s_lshl_b64 s[4:5], s[6:7], 10
	v_lshl_add_u64 v[4:5], v[4:5], 0, s[4:5]
	s_movk_i32 s4, 0x1000
	v_add_co_u32_e32 v6, vcc, s4, v4
	s_movk_i32 s4, 0x2000
	s_nop 0
	v_addc_co_u32_e32 v7, vcc, 0, v5, vcc
	v_add_co_u32_e32 v8, vcc, s4, v4
	s_movk_i32 s4, 0x3000
	s_nop 0
	v_addc_co_u32_e32 v9, vcc, 0, v5, vcc
	v_add_co_u32_e32 v10, vcc, s4, v4
	s_movk_i32 s4, 0x4000
	s_nop 0
	v_addc_co_u32_e32 v11, vcc, 0, v5, vcc
	v_add_co_u32_e32 v12, vcc, s4, v4
	s_movk_i32 s4, 0x5000
	s_nop 0
	v_addc_co_u32_e32 v13, vcc, 0, v5, vcc
	global_load_dword v94, v[4:5], off
	global_load_dword v93, v[4:5], off offset:1024
	global_load_dword v92, v[4:5], off offset:2048
	global_load_dword v90, v[4:5], off offset:3072
	global_load_dword v81, v[6:7], off offset:1024
	global_load_dword v79, v[6:7], off offset:2048
	global_load_dword v77, v[6:7], off offset:3072
	global_load_dword v70, v[10:11], off offset:1024
	global_load_dword v95, v[8:9], off offset:-4096
	global_load_dword v88, v[8:9], off
	global_load_dword v84, v[8:9], off offset:1024
	global_load_dword v82, v[8:9], off offset:2048
	global_load_dword v80, v[8:9], off offset:3072
	global_load_dword v78, v[12:13], off offset:-4096
	global_load_dword v72, v[12:13], off
	global_load_dword v71, v[12:13], off offset:1024
	v_add_co_u32_e32 v6, vcc, s4, v4
	s_lshl_b32 s14, s12, 6
	s_nop 0
	v_addc_co_u32_e32 v7, vcc, 0, v5, vcc
	s_movk_i32 s4, 0x6000
	v_readlane_b32 s15, v237, 59
	s_and_b32 s12, s14, 0xf000
	v_add_co_u32_e32 v8, vcc, s4, v4
	s_mulk_i32 s12, 0x1400
	s_nop 0
	v_addc_co_u32_e32 v9, vcc, 0, v5, vcc
	s_movk_i32 s4, 0x7000
	v_writelane_b32 v237, s14, 58
	s_and_b32 s13, s14, 0xfc0
	v_add_co_u32_e32 v4, vcc, s4, v4
	s_add_u32 s18, s16, s12
	global_load_dword v85, v[12:13], off offset:2048
	global_load_dword v83, v[12:13], off offset:3072
	global_load_dword v86, v[8:9], off offset:-4096
	global_load_dword v76, v[8:9], off
	global_load_dword v75, v[8:9], off offset:1024
	global_load_dword v74, v[8:9], off offset:2048
	global_load_dword v73, v[8:9], off offset:3072
	v_addc_co_u32_e32 v5, vcc, 0, v5, vcc
	global_load_dword v102, v[10:11], off offset:2048
	global_load_dword v101, v[10:11], off offset:3072
	global_load_dword v98, v[6:7], off offset:1024
	global_load_dword v97, v[6:7], off offset:2048
	global_load_dword v96, v[6:7], off offset:3072
	global_load_dword v91, v[4:5], off
	global_load_dword v89, v[4:5], off offset:1024
	global_load_dword v87, v[4:5], off offset:2048
	s_addc_u32 s19, s17, 0
	s_lshl_b32 s4, s88, 8
	s_ashr_i32 s5, s4, 31
	v_or_b32_sdwa v4, v62, s4 dst_sel:DWORD dst_unused:UNUSED_PAD src0_sel:BYTE_0 src1_sel:DWORD
	s_lshl_b64 s[4:5], s[4:5], 2
	s_add_u32 s6, s8, s4
	v_lshlrev_b32_e32 v1, 2, v62
	v_ashrrev_i32_e32 v5, 31, v4
	s_addc_u32 s7, s9, s5
	v_and_b32_e32 v1, 0xfc, v1
	v_lshl_add_u64 v[2:3], v[4:5], 2, v[2:3]
	v_lshlrev_b32_e32 v100, 2, v1
	s_add_u32 s4, s10, s4
	global_load_dword v99, v[2:3], off
	s_addc_u32 s5, s11, s5
	global_load_dwordx4 v[2:5], v100, s[6:7]
	global_load_dwordx4 v[6:9], v100, s[4:5]
	s_sub_i32 s24, s13, 30
	v_ashrrev_i32_e32 v10, 5, v62
	v_lshlrev_b32_e32 v67, 3, v62
	v_add_u32_e32 v10, s24, v10
	s_movk_i32 s4, 0xbc0
	v_writelane_b32 v237, s15, 59
	v_and_b32_e32 v68, 0xf8, v67
	v_cmp_gt_i32_e64 s[14:15], s4, v62
	v_cmp_lt_i32_e32 vcc, -1, v10
	s_and_b64 s[6:7], s[14:15], vcc
	v_mov_b32_e32 v34, 0
	v_lshlrev_b32_e32 v60, 1, v68
	v_mov_b32_e32 v54, 0
	v_mov_b32_e32 v55, 0
	v_mov_b32_e32 v56, 0
	v_mov_b32_e32 v57, 0
	v_mov_b32_e32 v50, 0
	v_mov_b32_e32 v51, 0
	v_mov_b32_e32 v52, 0
	v_mov_b32_e32 v53, 0
	s_and_saveexec_b64 s[4:5], s[6:7]
	s_cbranch_execz .LBB0_669
	v_mov_b64_e32 v[12:13], s[18:19]
	v_mad_u64_u32 v[10:11], s[6:7], v10, s93, v[12:13]
	v_mov_b32_e32 v61, v0
	v_lshl_add_u64 v[10:11], v[10:11], 0, v[60:61]
	v_add_co_u32_e32 v10, vcc, 0x9500000, v10
	s_nop 1
	v_addc_co_u32_e32 v11, vcc, 0, v11, vcc
	global_load_dwordx4 v[50:53], v[10:11], off offset:1536
	global_load_dwordx4 v[54:57], v[10:11], off offset:2048

; #define ATT_LOAD(t) do { kraw = *(const v4u*)(kp + (size_t)(t) * 64 * ZC); vraw = *(const v4u*)(vp + (size_t)(t) * 64 * ZC); \
;         if (!DIFF && tid < 64) ncv = ncp[(t) * 64 + tid]; } while (0)
; template <bool DIFF>
; __device__ __forceinline__ void attn_unit(CA& A, int l, int b, int hh, int qb, LAS unsigned char* lds, float lam, float lam_init) {
;     ...
;     for (int tt = 0; ; ++tt) {
;         const int t = DIFF ? tt : NT - 1 - tt;
;         const bool has_next = tt + 1 < NT;
;         const int buf = tt & 1, key0 = t * 64;
;         float nc_hi = 0.f;
;         if (has_next) { ATT_LOAD(DIFF ? t + 1 : t - 1); if (!DIFF) nc_hi = ncp[key0 - 1]; }
; __device__ __forceinline__ void mix_phase(CA& A0, int l, LAS unsigned char* lds) {
;     ...
;     for (;;) {
;         __syncthreads();
;         if (tid == 0) *slot = (int)atomicAdd(counter, 1u);
;         __syncthreads();
;         const int it = *slot;
.LBB0_747:
	s_cmp_lg_u32 s10, s11
	s_cbranch_scc1 .Lmy_pf_diff_skip
	s_mov_b64 s[38:39], exec
	v_readlane_b32 s40, v236, 5
	v_readlane_b32 s41, v236, 6
	s_nop 1
	s_and_b64 s[40:41], s[38:39], s[40:41]
	s_mov_b64 exec, s[40:41]
	s_cbranch_execz .Lmy_pf_diff_x
	v_readlane_b32 s40, v236, 3
	v_readlane_b32 s41, v236, 4
	v_mov_b32_e32 v239, 1
	s_nop 4
	global_atomic_add v239, v0, v239, s[40:41] sc0
.Lmy_pf_diff_x:
	s_mov_b64 exec, s[38:39]

; __global__ void __launch_bounds__(512, 2) fwd_kernel(Args A_unused) {
	.amdhsa_kernel _Z10fwd_kernel4Args
		.amdhsa_group_segment_fixed_size 0
		.amdhsa_private_segment_fixed_size 0
		.amdhsa_kernarg_size 472
		.amdhsa_user_sgpr_count 2
		.amdhsa_user_sgpr_dispatch_ptr 0
		.amdhsa_user_sgpr_queue_ptr 0
		.amdhsa_user_sgpr_kernarg_segment_ptr 1
		.amdhsa_user_sgpr_dispatch_id 0
		.amdhsa_user_sgpr_kernarg_preload_length 0
		.amdhsa_user_sgpr_kernarg_preload_offset 0
		.amdhsa_user_sgpr_private_segment_size 0
		.amdhsa_uses_dynamic_stack 0
		.amdhsa_enable_private_segment 0
		.amdhsa_system_sgpr_workgroup_id_x 1
		.amdhsa_system_sgpr_workgroup_id_y 0
		.amdhsa_system_sgpr_workgroup_id_z 0
		.amdhsa_system_sgpr_workgroup_info 0
		.amdhsa_system_vgpr_workitem_id 2
		.amdhsa_next_free_vgpr 240
		.amdhsa_next_free_sgpr 100
		.amdhsa_accum_offset 240
		.amdhsa_reserve_vcc 1
		.amdhsa_float_round_mode_32 0
		.amdhsa_float_round_mode_16_64 0
		.amdhsa_float_denorm_mode_32 3
		.amdhsa_float_denorm_mode_16_64 3
		.amdhsa_dx10_clamp 1
		.amdhsa_ieee_mode 1
		.amdhsa_fp16_overflow 0
		.amdhsa_tg_split 0
		.amdhsa_exception_fp_ieee_invalid_op 0
		.amdhsa_exception_fp_denorm_src 0
		.amdhsa_exception_fp_ieee_div_zero 0
		.amdhsa_exception_fp_ieee_overflow 0
		.amdhsa_exception_fp_ieee_underflow 0
		.amdhsa_exception_fp_ieee_inexact 0
		.amdhsa_exception_int_div_zero 0
	.end_amdhsa_kernel

; __global__ void __launch_bounds__(512, 2) fwd_kernel(Args A_unused) {
amdhsa.kernels:
  - .agpr_count:     0
    .args:
      - .offset:         0
        .size:           216
        .value_kind:     by_value
      - .offset:         216
        .size:           4
        .value_kind:     hidden_block_count_x
      - .offset:         220
        .size:           4
        .value_kind:     hidden_block_count_y
      - .offset:         224
        .size:           4
        .value_kind:     hidden_block_count_z
      - .offset:         228
        .size:           2
        .value_kind:     hidden_group_size_x
      - .offset:         230
        .size:           2
        .value_kind:     hidden_group_size_y
      - .offset:         232
        .size:           2
        .value_kind:     hidden_group_size_z
      - .offset:         234
        .size:           2
        .value_kind:     hidden_remainder_x
      - .offset:         236
        .size:           2
        .value_kind:     hidden_remainder_y
      - .offset:         238
        .size:           2
        .value_kind:     hidden_remainder_z
      - .offset:         256
        .size:           8
        .value_kind:     hidden_global_offset_x
      - .offset:         264
        .size:           8
        .value_kind:     hidden_global_offset_y
      - .offset:         272
        .size:           8
        .value_kind:     hidden_global_offset_z
      - .offset:         280
        .size:           2
        .value_kind:     hidden_grid_dims
      - .offset:         304
        .size:           8
        .value_kind:     hidden_multigrid_sync_arg
      - .offset:         336
        .size:           4
        .value_kind:     hidden_dynamic_lds_size
    .group_segment_fixed_size: 0
    .kernarg_segment_align: 8
    .kernarg_segment_size: 472
    .language:       OpenCL C
    .language_version:
      - 2
      - 0
    .max_flat_workgroup_size: 512
    .name:           _Z10fwd_kernel4Args
    .private_segment_fixed_size: 0
    .sgpr_count:     106
    .sgpr_spill_count: 179
    .symbol:         _Z10fwd_kernel4Args.kd
    .uniform_work_group_size: 1
    .uses_dynamic_stack: false
    .vgpr_count:     240
    .vgpr_spill_count: 0
    .wavefront_size: 64
